# write-through sc1 on dwordx4 GEMM epilogue stores (EpiStore+EpiResid) to cheapen barrier release fence
# baseline (speedup 1.0000x reference)
.LBB0_857:
	v_lshl_add_u32 v172, s76, 8, v33
	v_lshl_or_b32 v173, s27, 8, v161
	v_lshlrev_b32_e32 v164, 2, v186
	v_lshlrev_b32_e32 v163, 2, v187
	v_lshlrev_b32_e32 v154, 12, v172
	v_lshl_add_u32 v154, v173, 1, v154
	v_add_u32_e32 v155, 0x10000, v154
	v_add_u32_e32 v156, 0x20000, v154
	v_add_u32_e32 v157, 0x30000, v154
	v_add_u32_e32 v158, 0x80000, v154
	v_add_u32_e32 v159, 0x90000, v154
	v_add_u32_e32 v168, 0xa0000, v154
	v_add_u32_e32 v169, 0xb0000, v154
	global_load_dwordx4 v[192:195], v154, s[12:13]
	global_load_dwordx4 v[196:199], v154, s[12:13] offset:256
	global_load_dwordx4 v[200:203], v155, s[12:13]
	global_load_dwordx4 v[204:207], v155, s[12:13] offset:256
	global_load_dwordx4 v[208:211], v156, s[12:13]
	global_load_dwordx4 v[212:215], v156, s[12:13] offset:256
	global_load_dwordx4 v[216:219], v157, s[12:13]
	global_load_dwordx4 v[220:223], v157, s[12:13] offset:256
	global_load_dwordx4 v[224:227], v158, s[12:13]
	global_load_dwordx4 v[228:231], v158, s[12:13] offset:256
	global_load_dwordx4 v[232:235], v159, s[12:13]
	global_load_dwordx4 v[236:239], v159, s[12:13] offset:256
	global_load_dwordx4 v[240:243], v168, s[12:13]
	global_load_dwordx4 v[244:247], v168, s[12:13] offset:256
	global_load_dwordx4 v[136:139], v169, s[12:13]
	global_load_dwordx4 v[140:143], v169, s[12:13] offset:256
	s_lshl_b32 s96, s27, 4
	s_lshl_b32 s97, s55, 2
	s_add_i32 s96, s96, s97
	v_lshl_add_u32 v177, v172, 7, s96
	s_waitcnt vmcnt(15)
	v_lshlrev_b32_e32 v172, 16, v192
	v_and_b32_e32 v173, 0xffff0000, v192
	v_lshlrev_b32_e32 v174, 16, v193
	v_and_b32_e32 v175, 0xffff0000, v193
	v_lshlrev_b32_e32 v192, 16, v194
	v_and_b32_e32 v193, 0xffff0000, v194
	v_lshlrev_b32_e32 v194, 16, v195
	v_and_b32_e32 v195, 0xffff0000, v195
	v_pk_add_f32 v[132:133], v[132:133], v[172:173]
	v_pk_add_f32 v[134:135], v[134:135], v[174:175]
	v_pk_add_f32 v[128:129], v[128:129], v[192:193]
	v_pk_add_f32 v[130:131], v[130:131], v[194:195]
	v_cvt_pk_bf16_f32 v172, v132, v133
	v_cvt_pk_bf16_f32 v173, v134, v135
	v_cvt_pk_bf16_f32 v174, v128, v129
	v_cvt_pk_bf16_f32 v175, v130, v131
	global_store_dwordx4 v154, v[172:175], s[12:13] sc1
	v_mul_f32_e32 v192, v133, v133
	v_mul_f32_e32 v193, v135, v135
	v_fmac_f32_e32 v192, v132, v132
	v_fmac_f32_e32 v193, v134, v134
	v_add_f32_e32 v192, v192, v193
	v_mul_f32_e32 v193, v129, v129
	v_mul_f32_e32 v194, v131, v131
	v_fmac_f32_e32 v193, v128, v128
	v_fmac_f32_e32 v194, v130, v130
	v_add_f32_e32 v193, v193, v194
	v_add_f32_e32 v176, v192, v193
	s_waitcnt vmcnt(15)
	v_lshlrev_b32_e32 v128, 16, v196
	v_and_b32_e32 v129, 0xffff0000, v196
	v_lshlrev_b32_e32 v130, 16, v197
	v_and_b32_e32 v131, 0xffff0000, v197
	v_lshlrev_b32_e32 v196, 16, v198
	v_and_b32_e32 v197, 0xffff0000, v198
	v_lshlrev_b32_e32 v198, 16, v199
	v_and_b32_e32 v199, 0xffff0000, v199
	v_pk_add_f32 v[124:125], v[124:125], v[128:129]
	v_pk_add_f32 v[126:127], v[126:127], v[130:131]
	v_pk_add_f32 v[120:121], v[120:121], v[196:197]
	v_pk_add_f32 v[122:123], v[122:123], v[198:199]
	v_cvt_pk_bf16_f32 v128, v124, v125
	v_cvt_pk_bf16_f32 v129, v126, v127
	v_cvt_pk_bf16_f32 v130, v120, v121
	v_cvt_pk_bf16_f32 v131, v122, v123
	global_store_dwordx4 v154, v[128:131], s[12:13] offset:256 sc1
	v_mul_f32_e32 v196, v125, v125
	v_mul_f32_e32 v197, v127, v127
	v_fmac_f32_e32 v196, v124, v124
	v_fmac_f32_e32 v197, v126, v126
	v_add_f32_e32 v196, v196, v197
	v_mul_f32_e32 v197, v121, v121
	v_mul_f32_e32 v198, v123, v123
	v_fmac_f32_e32 v197, v120, v120
	v_fmac_f32_e32 v198, v122, v122
	v_add_f32_e32 v197, v197, v198
	v_add_f32_e32 v196, v196, v197
	v_add_f32_e32 v124, v176, v196
	s_waitcnt vmcnt(15)
	v_lshlrev_b32_e32 v120, 16, v200
	v_and_b32_e32 v121, 0xffff0000, v200
	v_lshlrev_b32_e32 v122, 16, v201
	v_and_b32_e32 v123, 0xffff0000, v201
	v_lshlrev_b32_e32 v200, 16, v202
	v_and_b32_e32 v201, 0xffff0000, v202
	v_lshlrev_b32_e32 v202, 16, v203
	v_and_b32_e32 v203, 0xffff0000, v203
	v_pk_add_f32 v[116:117], v[116:117], v[120:121]
	v_pk_add_f32 v[118:119], v[118:119], v[122:123]
	v_pk_add_f32 v[112:113], v[112:113], v[200:201]
	v_pk_add_f32 v[114:115], v[114:115], v[202:203]
	v_cvt_pk_bf16_f32 v120, v116, v117
	v_cvt_pk_bf16_f32 v121, v118, v119
	v_cvt_pk_bf16_f32 v122, v112, v113
	v_cvt_pk_bf16_f32 v123, v114, v115
	global_store_dwordx4 v155, v[120:123], s[12:13] sc1
	v_mul_f32_e32 v200, v117, v117
	v_mul_f32_e32 v201, v119, v119
	v_fmac_f32_e32 v200, v116, v116
	v_fmac_f32_e32 v201, v118, v118
	v_add_f32_e32 v200, v200, v201
	v_mul_f32_e32 v201, v113, v113
	v_mul_f32_e32 v202, v115, v115
	v_fmac_f32_e32 v201, v112, v112
	v_fmac_f32_e32 v202, v114, v114
	v_add_f32_e32 v201, v201, v202
	v_add_f32_e32 v176, v200, v201
	s_waitcnt vmcnt(15)
	v_lshlrev_b32_e32 v112, 16, v204
	v_and_b32_e32 v113, 0xffff0000, v204
	v_lshlrev_b32_e32 v114, 16, v205
	v_and_b32_e32 v115, 0xffff0000, v205
	v_lshlrev_b32_e32 v204, 16, v206
	v_and_b32_e32 v205, 0xffff0000, v206
	v_lshlrev_b32_e32 v206, 16, v207
	v_and_b32_e32 v207, 0xffff0000, v207
	v_pk_add_f32 v[108:109], v[108:109], v[112:113]
	v_pk_add_f32 v[110:111], v[110:111], v[114:115]
	v_pk_add_f32 v[104:105], v[104:105], v[204:205]
	v_pk_add_f32 v[106:107], v[106:107], v[206:207]
	v_cvt_pk_bf16_f32 v112, v108, v109
	v_cvt_pk_bf16_f32 v113, v110, v111
	v_cvt_pk_bf16_f32 v114, v104, v105
	v_cvt_pk_bf16_f32 v115, v106, v107
	global_store_dwordx4 v155, v[112:115], s[12:13] offset:256 sc1
	v_mul_f32_e32 v204, v109, v109
	v_mul_f32_e32 v205, v111, v111
	v_fmac_f32_e32 v204, v108, v108
	v_fmac_f32_e32 v205, v110, v110
	v_add_f32_e32 v204, v204, v205
	v_mul_f32_e32 v205, v105, v105
	v_mul_f32_e32 v206, v107, v107
	v_fmac_f32_e32 v205, v104, v104
	v_fmac_f32_e32 v206, v106, v106
	v_add_f32_e32 v205, v205, v206
	v_add_f32_e32 v204, v204, v205
	v_add_f32_e32 v108, v176, v204
	s_waitcnt vmcnt(15)
	v_lshlrev_b32_e32 v104, 16, v208
	v_and_b32_e32 v105, 0xffff0000, v208
	v_lshlrev_b32_e32 v106, 16, v209
	v_and_b32_e32 v107, 0xffff0000, v209
	v_lshlrev_b32_e32 v208, 16, v210
	v_and_b32_e32 v209, 0xffff0000, v210
	v_lshlrev_b32_e32 v210, 16, v211
	v_and_b32_e32 v211, 0xffff0000, v211
	v_pk_add_f32 v[100:101], v[100:101], v[104:105]
	v_pk_add_f32 v[102:103], v[102:103], v[106:107]
	v_pk_add_f32 v[96:97], v[96:97], v[208:209]
	v_pk_add_f32 v[98:99], v[98:99], v[210:211]
	v_cvt_pk_bf16_f32 v104, v100, v101
	v_cvt_pk_bf16_f32 v105, v102, v103
	v_cvt_pk_bf16_f32 v106, v96, v97
	v_cvt_pk_bf16_f32 v107, v98, v99
	global_store_dwordx4 v156, v[104:107], s[12:13] sc1
	v_mul_f32_e32 v208, v101, v101
	v_mul_f32_e32 v209, v103, v103
	v_fmac_f32_e32 v208, v100, v100
	v_fmac_f32_e32 v209, v102, v102
	v_add_f32_e32 v208, v208, v209
	v_mul_f32_e32 v209, v97, v97
	v_mul_f32_e32 v210, v99, v99
	v_fmac_f32_e32 v209, v96, v96
	v_fmac_f32_e32 v210, v98, v98
	v_add_f32_e32 v209, v209, v210
	v_add_f32_e32 v176, v208, v209
	s_waitcnt vmcnt(15)
	v_lshlrev_b32_e32 v96, 16, v212
	v_and_b32_e32 v97, 0xffff0000, v212
	v_lshlrev_b32_e32 v98, 16, v213
	v_and_b32_e32 v99, 0xffff0000, v213
	v_lshlrev_b32_e32 v212, 16, v214
	v_and_b32_e32 v213, 0xffff0000, v214
	v_lshlrev_b32_e32 v214, 16, v215
	v_and_b32_e32 v215, 0xffff0000, v215
	v_pk_add_f32 v[92:93], v[92:93], v[96:97]
	v_pk_add_f32 v[94:95], v[94:95], v[98:99]
	v_pk_add_f32 v[88:89], v[88:89], v[212:213]
	v_pk_add_f32 v[90:91], v[90:91], v[214:215]
	v_cvt_pk_bf16_f32 v96, v92, v93
	v_cvt_pk_bf16_f32 v97, v94, v95
	v_cvt_pk_bf16_f32 v98, v88, v89
	v_cvt_pk_bf16_f32 v99, v90, v91
	global_store_dwordx4 v156, v[96:99], s[12:13] offset:256 sc1
	v_mul_f32_e32 v212, v93, v93
	v_mul_f32_e32 v213, v95, v95
	v_fmac_f32_e32 v212, v92, v92
	v_fmac_f32_e32 v213, v94, v94
	v_add_f32_e32 v212, v212, v213
	v_mul_f32_e32 v213, v89, v89
	v_mul_f32_e32 v214, v91, v91
	v_fmac_f32_e32 v213, v88, v88
	v_fmac_f32_e32 v214, v90, v90
	v_add_f32_e32 v213, v213, v214
	v_add_f32_e32 v212, v212, v213
	v_add_f32_e32 v92, v176, v212
	s_waitcnt vmcnt(15)
	v_lshlrev_b32_e32 v88, 16, v216
	v_and_b32_e32 v89, 0xffff0000, v216
	v_lshlrev_b32_e32 v90, 16, v217
	v_and_b32_e32 v91, 0xffff0000, v217
	v_lshlrev_b32_e32 v216, 16, v218
	v_and_b32_e32 v217, 0xffff0000, v218
	v_lshlrev_b32_e32 v218, 16, v219
	v_and_b32_e32 v219, 0xffff0000, v219
	v_pk_add_f32 v[84:85], v[84:85], v[88:89]
	v_pk_add_f32 v[86:87], v[86:87], v[90:91]
	v_pk_add_f32 v[80:81], v[80:81], v[216:217]
	v_pk_add_f32 v[82:83], v[82:83], v[218:219]
	v_cvt_pk_bf16_f32 v88, v84, v85
	v_cvt_pk_bf16_f32 v89, v86, v87
	v_cvt_pk_bf16_f32 v90, v80, v81
	v_cvt_pk_bf16_f32 v91, v82, v83
	global_store_dwordx4 v157, v[88:91], s[12:13] sc1
	v_mul_f32_e32 v216, v85, v85
	v_mul_f32_e32 v217, v87, v87
	v_fmac_f32_e32 v216, v84, v84
	v_fmac_f32_e32 v217, v86, v86
	v_add_f32_e32 v216, v216, v217
	v_mul_f32_e32 v217, v81, v81
	v_mul_f32_e32 v218, v83, v83
	v_fmac_f32_e32 v217, v80, v80
	v_fmac_f32_e32 v218, v82, v82
	v_add_f32_e32 v217, v217, v218
	v_add_f32_e32 v176, v216, v217
	s_waitcnt vmcnt(15)
	v_lshlrev_b32_e32 v80, 16, v220
	v_and_b32_e32 v81, 0xffff0000, v220
	v_lshlrev_b32_e32 v82, 16, v221
	v_and_b32_e32 v83, 0xffff0000, v221
	v_lshlrev_b32_e32 v220, 16, v222
	v_and_b32_e32 v221, 0xffff0000, v222
	v_lshlrev_b32_e32 v222, 16, v223
	v_and_b32_e32 v223, 0xffff0000, v223
	v_pk_add_f32 v[76:77], v[76:77], v[80:81]
	v_pk_add_f32 v[78:79], v[78:79], v[82:83]
	v_pk_add_f32 v[72:73], v[72:73], v[220:221]
	v_pk_add_f32 v[74:75], v[74:75], v[222:223]
	v_cvt_pk_bf16_f32 v80, v76, v77
	v_cvt_pk_bf16_f32 v81, v78, v79
	v_cvt_pk_bf16_f32 v82, v72, v73
	v_cvt_pk_bf16_f32 v83, v74, v75
	global_store_dwordx4 v157, v[80:83], s[12:13] offset:256 sc1
	v_mul_f32_e32 v220, v77, v77
	v_mul_f32_e32 v221, v79, v79
	v_fmac_f32_e32 v220, v76, v76
	v_fmac_f32_e32 v221, v78, v78
	v_add_f32_e32 v220, v220, v221
	v_mul_f32_e32 v221, v73, v73
	v_mul_f32_e32 v222, v75, v75
	v_fmac_f32_e32 v221, v72, v72
	v_fmac_f32_e32 v222, v74, v74
	v_add_f32_e32 v221, v221, v222
	v_add_f32_e32 v220, v220, v221
	v_add_f32_e32 v76, v176, v220
	s_waitcnt vmcnt(15)
	v_lshlrev_b32_e32 v72, 16, v224
	v_and_b32_e32 v73, 0xffff0000, v224
	v_lshlrev_b32_e32 v74, 16, v225
	v_and_b32_e32 v75, 0xffff0000, v225
	v_lshlrev_b32_e32 v224, 16, v226
	v_and_b32_e32 v225, 0xffff0000, v226
	v_lshlrev_b32_e32 v226, 16, v227
	v_and_b32_e32 v227, 0xffff0000, v227
	v_pk_add_f32 v[68:69], v[68:69], v[72:73]
	v_pk_add_f32 v[70:71], v[70:71], v[74:75]
	v_pk_add_f32 v[64:65], v[64:65], v[224:225]
	v_pk_add_f32 v[66:67], v[66:67], v[226:227]
	v_cvt_pk_bf16_f32 v72, v68, v69
	v_cvt_pk_bf16_f32 v73, v70, v71
	v_cvt_pk_bf16_f32 v74, v64, v65
	v_cvt_pk_bf16_f32 v75, v66, v67
	global_store_dwordx4 v158, v[72:75], s[12:13] sc1
	v_mul_f32_e32 v224, v69, v69
	v_mul_f32_e32 v225, v71, v71
	v_fmac_f32_e32 v224, v68, v68
	v_fmac_f32_e32 v225, v70, v70
	v_add_f32_e32 v224, v224, v225
	v_mul_f32_e32 v225, v65, v65
	v_mul_f32_e32 v226, v67, v67
	v_fmac_f32_e32 v225, v64, v64
	v_fmac_f32_e32 v226, v66, v66
	v_add_f32_e32 v225, v225, v226
	v_add_f32_e32 v176, v224, v225
	s_waitcnt vmcnt(15)
	v_lshlrev_b32_e32 v64, 16, v228
	v_and_b32_e32 v65, 0xffff0000, v228
	v_lshlrev_b32_e32 v66, 16, v229
	v_and_b32_e32 v67, 0xffff0000, v229
	v_lshlrev_b32_e32 v228, 16, v230
	v_and_b32_e32 v229, 0xffff0000, v230
	v_lshlrev_b32_e32 v230, 16, v231
	v_and_b32_e32 v231, 0xffff0000, v231
	v_pk_add_f32 v[60:61], v[60:61], v[64:65]
	v_pk_add_f32 v[62:63], v[62:63], v[66:67]
	v_pk_add_f32 v[56:57], v[56:57], v[228:229]
	v_pk_add_f32 v[58:59], v[58:59], v[230:231]
	v_cvt_pk_bf16_f32 v64, v60, v61
	v_cvt_pk_bf16_f32 v65, v62, v63
	v_cvt_pk_bf16_f32 v66, v56, v57
	v_cvt_pk_bf16_f32 v67, v58, v59
	global_store_dwordx4 v158, v[64:67], s[12:13] offset:256 sc1
	v_mul_f32_e32 v228, v61, v61
	v_mul_f32_e32 v229, v63, v63
	v_fmac_f32_e32 v228, v60, v60
	v_fmac_f32_e32 v229, v62, v62
	v_add_f32_e32 v228, v228, v229
	v_mul_f32_e32 v229, v57, v57
	v_mul_f32_e32 v230, v59, v59
	v_fmac_f32_e32 v229, v56, v56
	v_fmac_f32_e32 v230, v58, v58
	v_add_f32_e32 v229, v229, v230
	v_add_f32_e32 v228, v228, v229
	v_add_f32_e32 v60, v176, v228
	s_waitcnt vmcnt(15)
	v_lshlrev_b32_e32 v56, 16, v232
	v_and_b32_e32 v57, 0xffff0000, v232
	v_lshlrev_b32_e32 v58, 16, v233
	v_and_b32_e32 v59, 0xffff0000, v233
	v_lshlrev_b32_e32 v232, 16, v234
	v_and_b32_e32 v233, 0xffff0000, v234
	v_lshlrev_b32_e32 v234, 16, v235
	v_and_b32_e32 v235, 0xffff0000, v235
	v_pk_add_f32 v[52:53], v[52:53], v[56:57]
	v_pk_add_f32 v[54:55], v[54:55], v[58:59]
	v_pk_add_f32 v[48:49], v[48:49], v[232:233]
	v_pk_add_f32 v[50:51], v[50:51], v[234:235]
	v_cvt_pk_bf16_f32 v56, v52, v53
	v_cvt_pk_bf16_f32 v57, v54, v55
	v_cvt_pk_bf16_f32 v58, v48, v49
	v_cvt_pk_bf16_f32 v59, v50, v51
	global_store_dwordx4 v159, v[56:59], s[12:13] sc1
	v_mul_f32_e32 v232, v53, v53
	v_mul_f32_e32 v233, v55, v55
	v_fmac_f32_e32 v232, v52, v52
	v_fmac_f32_e32 v233, v54, v54
	v_add_f32_e32 v232, v232, v233
	v_mul_f32_e32 v233, v49, v49
	v_mul_f32_e32 v234, v51, v51
	v_fmac_f32_e32 v233, v48, v48
	v_fmac_f32_e32 v234, v50, v50
	v_add_f32_e32 v233, v233, v234
	v_add_f32_e32 v176, v232, v233
	s_waitcnt vmcnt(15)
	v_lshlrev_b32_e32 v48, 16, v236
	v_and_b32_e32 v49, 0xffff0000, v236
	v_lshlrev_b32_e32 v50, 16, v237
	v_and_b32_e32 v51, 0xffff0000, v237
	v_lshlrev_b32_e32 v236, 16, v238
	v_and_b32_e32 v237, 0xffff0000, v238
	v_lshlrev_b32_e32 v238, 16, v239
	v_and_b32_e32 v239, 0xffff0000, v239
	v_pk_add_f32 v[44:45], v[44:45], v[48:49]
	v_pk_add_f32 v[46:47], v[46:47], v[50:51]
	v_pk_add_f32 v[40:41], v[40:41], v[236:237]
	v_pk_add_f32 v[42:43], v[42:43], v[238:239]
	v_cvt_pk_bf16_f32 v48, v44, v45
	v_cvt_pk_bf16_f32 v49, v46, v47
	v_cvt_pk_bf16_f32 v50, v40, v41
	v_cvt_pk_bf16_f32 v51, v42, v43
	global_store_dwordx4 v159, v[48:51], s[12:13] offset:256 sc1
	v_mul_f32_e32 v236, v45, v45
	v_mul_f32_e32 v237, v47, v47
	v_fmac_f32_e32 v236, v44, v44
	v_fmac_f32_e32 v237, v46, v46
	v_add_f32_e32 v236, v236, v237
	v_mul_f32_e32 v237, v41, v41
	v_mul_f32_e32 v238, v43, v43
	v_fmac_f32_e32 v237, v40, v40
	v_fmac_f32_e32 v238, v42, v42
	v_add_f32_e32 v237, v237, v238
	v_add_f32_e32 v236, v236, v237
	v_add_f32_e32 v44, v176, v236
	s_waitcnt vmcnt(15)
	v_lshlrev_b32_e32 v40, 16, v240
	v_and_b32_e32 v41, 0xffff0000, v240
	v_lshlrev_b32_e32 v42, 16, v241
	v_and_b32_e32 v43, 0xffff0000, v241
	v_lshlrev_b32_e32 v240, 16, v242
	v_and_b32_e32 v241, 0xffff0000, v242
	v_lshlrev_b32_e32 v242, 16, v243
	v_and_b32_e32 v243, 0xffff0000, v243
	v_pk_add_f32 v[28:29], v[28:29], v[40:41]
	v_pk_add_f32 v[30:31], v[30:31], v[42:43]
	v_pk_add_f32 v[24:25], v[24:25], v[240:241]
	v_pk_add_f32 v[26:27], v[26:27], v[242:243]
	v_cvt_pk_bf16_f32 v40, v28, v29
	v_cvt_pk_bf16_f32 v41, v30, v31
	v_cvt_pk_bf16_f32 v42, v24, v25
	v_cvt_pk_bf16_f32 v43, v26, v27
	global_store_dwordx4 v168, v[40:43], s[12:13] sc1
	v_mul_f32_e32 v240, v29, v29
	v_mul_f32_e32 v241, v31, v31
	v_fmac_f32_e32 v240, v28, v28
	v_fmac_f32_e32 v241, v30, v30
	v_add_f32_e32 v240, v240, v241
	v_mul_f32_e32 v241, v25, v25
	v_mul_f32_e32 v242, v27, v27
	v_fmac_f32_e32 v241, v24, v24
	v_fmac_f32_e32 v242, v26, v26
	v_add_f32_e32 v241, v241, v242
	v_add_f32_e32 v176, v240, v241
	s_waitcnt vmcnt(15)
	v_lshlrev_b32_e32 v24, 16, v244
	v_and_b32_e32 v25, 0xffff0000, v244
	v_lshlrev_b32_e32 v26, 16, v245
	v_and_b32_e32 v27, 0xffff0000, v245
	v_lshlrev_b32_e32 v244, 16, v246
	v_and_b32_e32 v245, 0xffff0000, v246
	v_lshlrev_b32_e32 v246, 16, v247
	v_and_b32_e32 v247, 0xffff0000, v247
	v_pk_add_f32 v[20:21], v[20:21], v[24:25]
	v_pk_add_f32 v[22:23], v[22:23], v[26:27]
	v_pk_add_f32 v[16:17], v[16:17], v[244:245]
	v_pk_add_f32 v[18:19], v[18:19], v[246:247]
	v_cvt_pk_bf16_f32 v24, v20, v21
	v_cvt_pk_bf16_f32 v25, v22, v23
	v_cvt_pk_bf16_f32 v26, v16, v17
	v_cvt_pk_bf16_f32 v27, v18, v19
	global_store_dwordx4 v168, v[24:27], s[12:13] offset:256 sc1
	v_mul_f32_e32 v244, v21, v21
	v_mul_f32_e32 v245, v23, v23
	v_fmac_f32_e32 v244, v20, v20
	v_fmac_f32_e32 v245, v22, v22
	v_add_f32_e32 v244, v244, v245
	v_mul_f32_e32 v245, v17, v17
	v_mul_f32_e32 v246, v19, v19
	v_fmac_f32_e32 v245, v16, v16
	v_fmac_f32_e32 v246, v18, v18
	v_add_f32_e32 v245, v245, v246
	v_add_f32_e32 v244, v244, v245
	v_add_f32_e32 v20, v176, v244
	s_waitcnt vmcnt(15)
	v_lshlrev_b32_e32 v16, 16, v136
	v_and_b32_e32 v17, 0xffff0000, v136
	v_lshlrev_b32_e32 v18, 16, v137
	v_and_b32_e32 v19, 0xffff0000, v137
	v_lshlrev_b32_e32 v136, 16, v138
	v_and_b32_e32 v137, 0xffff0000, v138
	v_lshlrev_b32_e32 v138, 16, v139
	v_and_b32_e32 v139, 0xffff0000, v139
	v_pk_add_f32 v[12:13], v[12:13], v[16:17]
	v_pk_add_f32 v[14:15], v[14:15], v[18:19]
	v_pk_add_f32 v[8:9], v[8:9], v[136:137]
	v_pk_add_f32 v[10:11], v[10:11], v[138:139]
	v_cvt_pk_bf16_f32 v16, v12, v13
	v_cvt_pk_bf16_f32 v17, v14, v15
	v_cvt_pk_bf16_f32 v18, v8, v9
	v_cvt_pk_bf16_f32 v19, v10, v11
	global_store_dwordx4 v169, v[16:19], s[12:13] sc1
	v_mul_f32_e32 v136, v13, v13
	v_mul_f32_e32 v137, v15, v15
	v_fmac_f32_e32 v136, v12, v12
	v_fmac_f32_e32 v137, v14, v14
	v_add_f32_e32 v136, v136, v137
	v_mul_f32_e32 v137, v9, v9
	v_mul_f32_e32 v138, v11, v11
	v_fmac_f32_e32 v137, v8, v8
	v_fmac_f32_e32 v138, v10, v10
	v_add_f32_e32 v137, v137, v138
	v_add_f32_e32 v176, v136, v137
	s_waitcnt vmcnt(15)
	v_lshlrev_b32_e32 v8, 16, v140
	v_and_b32_e32 v9, 0xffff0000, v140
	v_lshlrev_b32_e32 v10, 16, v141
	v_and_b32_e32 v11, 0xffff0000, v141
	v_lshlrev_b32_e32 v140, 16, v142
	v_and_b32_e32 v141, 0xffff0000, v142
	v_lshlrev_b32_e32 v142, 16, v143
	v_and_b32_e32 v143, 0xffff0000, v143
	v_pk_add_f32 v[4:5], v[4:5], v[8:9]
	v_pk_add_f32 v[6:7], v[6:7], v[10:11]
	v_pk_add_f32 v[0:1], v[0:1], v[140:141]
	v_pk_add_f32 v[2:3], v[2:3], v[142:143]
	v_cvt_pk_bf16_f32 v8, v4, v5
	v_cvt_pk_bf16_f32 v9, v6, v7
	v_cvt_pk_bf16_f32 v10, v0, v1
	v_cvt_pk_bf16_f32 v11, v2, v3
	global_store_dwordx4 v169, v[8:11], s[12:13] offset:256 sc1
	v_mul_f32_e32 v140, v5, v5
	v_mul_f32_e32 v141, v7, v7
	v_fmac_f32_e32 v140, v4, v4
	v_fmac_f32_e32 v141, v6, v6
	v_add_f32_e32 v140, v140, v141
	v_mul_f32_e32 v141, v1, v1
	v_mul_f32_e32 v142, v3, v3
	v_fmac_f32_e32 v141, v0, v0
	v_fmac_f32_e32 v142, v2, v2
	v_add_f32_e32 v141, v141, v142
	v_add_f32_e32 v140, v140, v141
	v_add_f32_e32 v4, v176, v140
	ds_bpermute_b32 v125, v164, v124
	ds_bpermute_b32 v109, v164, v108
	ds_bpermute_b32 v93, v164, v92
	ds_bpermute_b32 v77, v164, v76
	ds_bpermute_b32 v61, v164, v60
	ds_bpermute_b32 v45, v164, v44
	ds_bpermute_b32 v21, v164, v20
	ds_bpermute_b32 v5, v164, v4
	s_waitcnt lgkmcnt(0)
	v_add_f32_e32 v124, v124, v125
	v_add_f32_e32 v108, v108, v109
	v_add_f32_e32 v92, v92, v93
	v_add_f32_e32 v76, v76, v77
	v_add_f32_e32 v60, v60, v61
	v_add_f32_e32 v44, v44, v45
	v_add_f32_e32 v20, v20, v21
	v_add_f32_e32 v4, v4, v5
	ds_bpermute_b32 v125, v163, v124
	ds_bpermute_b32 v109, v163, v108
	ds_bpermute_b32 v93, v163, v92
	ds_bpermute_b32 v77, v163, v76
	ds_bpermute_b32 v61, v163, v60
	ds_bpermute_b32 v45, v163, v44
	ds_bpermute_b32 v21, v163, v20
	ds_bpermute_b32 v5, v163, v4
	v_add_u32_e32 v192, 0x1000, v177
	v_add_u32_e32 v193, 0x4000, v177
	v_add_u32_e32 v194, 0x5000, v177
	s_waitcnt lgkmcnt(0)
	s_and_saveexec_b64 s[24:25], s[36:37]
	s_cbranch_execz .LBB0_873
	v_add_f32_e32 v124, v124, v125
	v_add_f32_e32 v108, v108, v109
	v_add_f32_e32 v92, v92, v93
	v_add_f32_e32 v76, v76, v77
	v_add_f32_e32 v60, v60, v61
	v_add_f32_e32 v44, v44, v45
	v_add_f32_e32 v20, v20, v21
	v_add_f32_e32 v4, v4, v5
	global_store_dword v177, v124, s[42:43]
	global_store_dword v177, v108, s[42:43] offset:2048
	global_store_dword v192, v92, s[42:43]
	global_store_dword v192, v76, s[42:43] offset:2048
	global_store_dword v193, v60, s[42:43]
	global_store_dword v193, v44, s[42:43] offset:2048
	global_store_dword v194, v20, s[42:43]
	global_store_dword v194, v4, s[42:43] offset:2048

.LBB0_918:
	v_mad_u64_u32 v[138:139], s[0:1], v154, s89, 0
	v_mov_b32_e32 v140, v139
	v_lshl_or_b32 v136, s52, 8, v159
	v_mad_u64_u32 v[140:141], s[0:1], v155, s89, v[140:141]
	v_ashrrev_i32_e32 v137, 31, v136
	v_mov_b32_e32 v139, v140
	v_lshl_add_u64 v[138:139], v[138:139], 1, s[54:55]
	v_lshlrev_b64 v[162:163], 1, v[136:137]
	v_lshl_add_u64 v[136:137], v[138:139], 0, v[162:163]
	s_waitcnt vmcnt(0)
	v_pk_mul_f32 v[134:135], v[134:135], v[172:173] op_sel_hi:[1,0]
	v_pk_mul_f32 v[132:133], v[132:133], v[172:173] op_sel_hi:[1,0]
	v_pk_mul_f32 v[138:139], v[130:131], v[172:173] op_sel_hi:[1,0]
	v_pk_mul_f32 v[130:131], v[128:129], v[172:173] op_sel_hi:[1,0]
	v_cvt_pk_bf16_f32 v128, v132, v133
	v_cvt_pk_bf16_f32 v129, v134, v135
	v_cvt_pk_bf16_f32 v130, v130, v131
	v_cvt_pk_bf16_f32 v131, v138, v139
	global_store_dwordx4 v[136:137], v[128:131], off sc1
	v_pk_mul_f32 v[122:123], v[122:123], v[172:173] op_sel_hi:[1,0]
	v_pk_mul_f32 v[120:121], v[120:121], v[172:173] op_sel_hi:[1,0]
	v_pk_mul_f32 v[128:129], v[114:115], v[172:173] op_sel_hi:[1,0]
	v_pk_mul_f32 v[114:115], v[112:113], v[172:173] op_sel_hi:[1,0]
	v_cvt_pk_bf16_f32 v112, v120, v121
	v_cvt_pk_bf16_f32 v113, v122, v123
	v_cvt_pk_bf16_f32 v114, v114, v115
	v_cvt_pk_bf16_f32 v115, v128, v129
	global_store_dwordx4 v[136:137], v[112:115], off offset:256 sc1
	v_pk_mul_f32 v[118:119], v[118:119], v[170:171] op_sel_hi:[1,0]
	v_pk_mul_f32 v[116:117], v[116:117], v[170:171] op_sel_hi:[1,0]
	v_or_b32_e32 v112, 16, v154
	v_mad_i64_i32 v[112:113], s[0:1], v112, s89, 0
	v_lshl_add_u64 v[112:113], v[112:113], 1, s[54:55]
	v_lshl_add_u64 v[120:121], v[112:113], 0, v[162:163]
	v_pk_mul_f32 v[114:115], v[126:127], v[170:171] op_sel_hi:[1,0]
	v_pk_mul_f32 v[112:113], v[124:125], v[170:171] op_sel_hi:[1,0]
	v_pk_mul_f32 v[106:107], v[106:107], v[170:171] op_sel_hi:[1,0]
	v_cvt_pk_bf16_f32 v112, v112, v113
	v_cvt_pk_bf16_f32 v113, v114, v115
	v_cvt_pk_bf16_f32 v114, v116, v117
	v_cvt_pk_bf16_f32 v115, v118, v119
	global_store_dwordx4 v[120:121], v[112:115], off sc1
	v_pk_mul_f32 v[104:105], v[104:105], v[170:171] op_sel_hi:[1,0]
	v_pk_mul_f32 v[102:103], v[102:103], v[168:169] op_sel_hi:[1,0]
	v_pk_mul_f32 v[112:113], v[98:99], v[170:171] op_sel_hi:[1,0]
	v_pk_mul_f32 v[98:99], v[96:97], v[170:171] op_sel_hi:[1,0]
	v_cvt_pk_bf16_f32 v96, v104, v105
	v_cvt_pk_bf16_f32 v97, v106, v107
	v_cvt_pk_bf16_f32 v98, v98, v99
	v_cvt_pk_bf16_f32 v99, v112, v113
	global_store_dwordx4 v[120:121], v[96:99], off offset:256 sc1
	v_pk_mul_f32 v[100:101], v[100:101], v[168:169] op_sel_hi:[1,0]
	v_pk_mul_f32 v[90:91], v[90:91], v[168:169] op_sel_hi:[1,0]
	v_or_b32_e32 v96, 32, v154
	v_mad_i64_i32 v[96:97], s[0:1], v96, s89, 0
	v_lshl_add_u64 v[96:97], v[96:97], 1, s[54:55]
	v_lshl_add_u64 v[104:105], v[96:97], 0, v[162:163]
	v_pk_mul_f32 v[98:99], v[110:111], v[168:169] op_sel_hi:[1,0]
	v_pk_mul_f32 v[96:97], v[108:109], v[168:169] op_sel_hi:[1,0]
	v_pk_mul_f32 v[88:89], v[88:89], v[168:169] op_sel_hi:[1,0]
	v_cvt_pk_bf16_f32 v96, v96, v97
	v_cvt_pk_bf16_f32 v97, v98, v99
	v_cvt_pk_bf16_f32 v98, v100, v101
	v_cvt_pk_bf16_f32 v99, v102, v103
	global_store_dwordx4 v[104:105], v[96:99], off sc1
	v_pk_mul_f32 v[86:87], v[86:87], v[166:167] op_sel_hi:[1,0]
	v_pk_mul_f32 v[84:85], v[84:85], v[166:167] op_sel_hi:[1,0]
	v_pk_mul_f32 v[96:97], v[82:83], v[168:169] op_sel_hi:[1,0]
	v_pk_mul_f32 v[82:83], v[80:81], v[168:169] op_sel_hi:[1,0]
	v_cvt_pk_bf16_f32 v80, v88, v89
	v_cvt_pk_bf16_f32 v81, v90, v91
	v_cvt_pk_bf16_f32 v82, v82, v83
	v_cvt_pk_bf16_f32 v83, v96, v97
	global_store_dwordx4 v[104:105], v[80:83], off offset:256 sc1
	v_pk_mul_f32 v[78:79], v[78:79], v[166:167] op_sel_hi:[1,0]
	v_pk_mul_f32 v[76:77], v[76:77], v[166:167] op_sel_hi:[1,0]
	v_or_b32_e32 v80, 48, v154
	v_mad_i64_i32 v[80:81], s[0:1], v80, s89, 0
	v_lshl_add_u64 v[80:81], v[80:81], 1, s[54:55]
	v_lshl_add_u64 v[88:89], v[80:81], 0, v[162:163]
	v_pk_mul_f32 v[82:83], v[94:95], v[166:167] op_sel_hi:[1,0]
	v_pk_mul_f32 v[80:81], v[92:93], v[166:167] op_sel_hi:[1,0]
	v_add_u32_e32 v143, 0x80, v154
	v_cvt_pk_bf16_f32 v80, v80, v81
	v_cvt_pk_bf16_f32 v81, v82, v83
	v_cvt_pk_bf16_f32 v82, v84, v85
	v_cvt_pk_bf16_f32 v83, v86, v87
	global_store_dwordx4 v[88:89], v[80:83], off sc1
	v_pk_mul_f32 v[70:71], v[70:71], v[164:165] op_sel_hi:[1,0]
	v_pk_mul_f32 v[68:69], v[68:69], v[164:165] op_sel_hi:[1,0]
	v_pk_mul_f32 v[80:81], v[74:75], v[166:167] op_sel_hi:[1,0]
	v_pk_mul_f32 v[74:75], v[72:73], v[166:167] op_sel_hi:[1,0]
	v_cvt_pk_bf16_f32 v72, v76, v77
	v_cvt_pk_bf16_f32 v73, v78, v79
	v_cvt_pk_bf16_f32 v74, v74, v75
	v_cvt_pk_bf16_f32 v75, v80, v81
	global_store_dwordx4 v[88:89], v[72:75], off offset:256 sc1
	v_pk_mul_f32 v[58:59], v[58:59], v[164:165] op_sel_hi:[1,0]
	v_pk_mul_f32 v[56:57], v[56:57], v[164:165] op_sel_hi:[1,0]
	v_mad_i64_i32 v[72:73], s[0:1], v143, s89, 0
	v_lshl_add_u64 v[72:73], v[72:73], 1, s[54:55]
	v_pk_mul_f32 v[74:75], v[66:67], v[164:165] op_sel_hi:[1,0]
	v_pk_mul_f32 v[66:67], v[64:65], v[164:165] op_sel_hi:[1,0]
	v_lshl_add_u64 v[72:73], v[72:73], 0, v[162:163]
	v_cvt_pk_bf16_f32 v64, v68, v69
	v_cvt_pk_bf16_f32 v65, v70, v71
	v_cvt_pk_bf16_f32 v66, v66, v67
	v_cvt_pk_bf16_f32 v67, v74, v75
	global_store_dwordx4 v[72:73], v[64:67], off sc1
	v_pk_mul_f32 v[54:55], v[54:55], v[160:161] op_sel_hi:[1,0]
	v_pk_mul_f32 v[52:53], v[52:53], v[160:161] op_sel_hi:[1,0]
	v_pk_mul_f32 v[64:65], v[50:51], v[164:165] op_sel_hi:[1,0]
	v_pk_mul_f32 v[50:51], v[48:49], v[164:165] op_sel_hi:[1,0]
	v_cvt_pk_bf16_f32 v48, v56, v57
	v_cvt_pk_bf16_f32 v49, v58, v59
	v_cvt_pk_bf16_f32 v50, v50, v51
	v_cvt_pk_bf16_f32 v51, v64, v65
	global_store_dwordx4 v[72:73], v[48:51], off offset:256 sc1
	v_pk_mul_f32 v[42:43], v[42:43], v[160:161] op_sel_hi:[1,0]
	v_pk_mul_f32 v[40:41], v[40:41], v[160:161] op_sel_hi:[1,0]
	v_add_u32_e32 v48, 0x90, v154
	v_mad_i64_i32 v[48:49], s[0:1], v48, s89, 0
	v_lshl_add_u64 v[48:49], v[48:49], 1, s[54:55]
	v_lshl_add_u64 v[56:57], v[48:49], 0, v[162:163]
	v_pk_mul_f32 v[50:51], v[62:63], v[160:161] op_sel_hi:[1,0]
	v_pk_mul_f32 v[48:49], v[60:61], v[160:161] op_sel_hi:[1,0]
	v_pk_mul_f32 v[30:31], v[30:31], v[158:159] op_sel_hi:[1,0]
	v_cvt_pk_bf16_f32 v48, v48, v49
	v_cvt_pk_bf16_f32 v49, v50, v51
	v_cvt_pk_bf16_f32 v50, v52, v53
	v_cvt_pk_bf16_f32 v51, v54, v55
	global_store_dwordx4 v[56:57], v[48:51], off sc1
	v_pk_mul_f32 v[28:29], v[28:29], v[158:159] op_sel_hi:[1,0]
	v_pk_mul_f32 v[18:19], v[18:19], v[158:159] op_sel_hi:[1,0]
	v_pk_mul_f32 v[48:49], v[26:27], v[160:161] op_sel_hi:[1,0]
	v_pk_mul_f32 v[26:27], v[24:25], v[160:161] op_sel_hi:[1,0]
	v_cvt_pk_bf16_f32 v24, v40, v41
	v_cvt_pk_bf16_f32 v25, v42, v43
	v_cvt_pk_bf16_f32 v26, v26, v27
	v_cvt_pk_bf16_f32 v27, v48, v49
	global_store_dwordx4 v[56:57], v[24:27], off offset:256 sc1
	v_pk_mul_f32 v[16:17], v[16:17], v[158:159] op_sel_hi:[1,0]
	v_add_u32_e32 v142, 0xb0, v154
	v_add_u32_e32 v24, 0xa0, v154
	v_mad_i64_i32 v[24:25], s[0:1], v24, s89, 0
	v_lshl_add_u64 v[24:25], v[24:25], 1, s[54:55]
	v_lshl_add_u64 v[40:41], v[24:25], 0, v[162:163]
	v_pk_mul_f32 v[26:27], v[46:47], v[158:159] op_sel_hi:[1,0]
	v_pk_mul_f32 v[24:25], v[44:45], v[158:159] op_sel_hi:[1,0]
	v_pk_mul_f32 v[14:15], v[14:15], v[156:157] op_sel_hi:[1,0]
	v_cvt_pk_bf16_f32 v24, v24, v25
	v_cvt_pk_bf16_f32 v25, v26, v27
	v_cvt_pk_bf16_f32 v26, v28, v29
	v_cvt_pk_bf16_f32 v27, v30, v31
	global_store_dwordx4 v[40:41], v[24:27], off sc1
	v_pk_mul_f32 v[12:13], v[12:13], v[156:157] op_sel_hi:[1,0]
	v_pk_mul_f32 v[6:7], v[6:7], v[156:157] op_sel_hi:[1,0]
	v_pk_mul_f32 v[24:25], v[10:11], v[158:159] op_sel_hi:[1,0]
	v_pk_mul_f32 v[10:11], v[8:9], v[158:159] op_sel_hi:[1,0]
	v_cvt_pk_bf16_f32 v8, v16, v17
	v_cvt_pk_bf16_f32 v9, v18, v19
	v_cvt_pk_bf16_f32 v10, v10, v11
	v_cvt_pk_bf16_f32 v11, v24, v25
	global_store_dwordx4 v[40:41], v[8:11], off offset:256 sc1
	v_pk_mul_f32 v[4:5], v[4:5], v[156:157] op_sel_hi:[1,0]
	s_and_b64 vcc, exec, s[2:3]
	v_mad_i64_i32 v[8:9], s[0:1], v142, s89, 0
	v_lshl_add_u64 v[8:9], v[8:9], 1, s[54:55]
	v_lshl_add_u64 v[16:17], v[8:9], 0, v[162:163]
	v_pk_mul_f32 v[10:11], v[22:23], v[156:157] op_sel_hi:[1,0]
	v_pk_mul_f32 v[8:9], v[20:21], v[156:157] op_sel_hi:[1,0]
	s_mov_b64 s[0:1], -1
	v_cvt_pk_bf16_f32 v8, v8, v9
	v_cvt_pk_bf16_f32 v9, v10, v11
	v_cvt_pk_bf16_f32 v10, v12, v13
	v_cvt_pk_bf16_f32 v11, v14, v15
	global_store_dwordx4 v[16:17], v[8:11], off sc1
	s_nop 1
	v_pk_mul_f32 v[8:9], v[2:3], v[156:157] op_sel_hi:[1,0]
	v_pk_mul_f32 v[2:3], v[0:1], v[156:157] op_sel_hi:[1,0]
	v_cvt_pk_bf16_f32 v0, v4, v5
	v_cvt_pk_bf16_f32 v1, v6, v7
	v_cvt_pk_bf16_f32 v2, v2, v3
	v_cvt_pk_bf16_f32 v3, v8, v9
	global_store_dwordx4 v[16:17], v[0:3], off offset:256 sc1
	s_cbranch_vccnz .LBB0_891
	s_andn2_b64 vcc, exec, s[30:31]
	s_cbranch_vccnz .LBB0_890
	s_barrier
	s_branch .LBB0_890
